# retention: K-tile DMAs issued by waves 0-3 after the P barrier and by waves 4-7 after their partner-P MFMAs, so the two waves of a SIMD do not block on the DMA queue at the same time
# baseline (speedup 1.0000x reference)
; #define LAS __attribute__((address_space(3)))
; #define RT_VRD(dst, g) do { _Pragma("unroll") for (int j_ = 0; j_ < 2; ++j_) { const int jj_ = 2 * ((g) & 1) + j_; dst[j_] = *(const LAS bf16x8*)(vb + ((g) >> 1) * 4096 + (((4 * (jj_ >> 1) + 2 * (jj_ & 1) + hh) << 4) ^ m4)); } } while (0)
; #define RT_VMM(src, g) do { _Pragma("unroll") for (int j_ = 0; j_ < 2; ++j_) { const int jj_ = 2 * ((g) & 1) + j_; oacc[(g) >> 1] = __builtin_amdgcn_mfma_f32_32x32x16_bf16(src[j_], pf[jj_ >> 1][jj_ & 1], oacc[(g) >> 1], 0, 0, 0); } } while (0)
; __device__ __forceinline__ void p2_ret(const Frame& F, ArgsP a, int layer) {
;     ...
;                 { bf16x8 pf[2][2];
; #pragma unroll
;                   for (int kb2 = 0; kb2 < 2; ++kb2)
; #pragma unroll
;                       for (int s = 0; s < 2; ++s) pf[kb2][s] = *(const LAS bf16x8*)(lds + RT_P + ((wr * 2 + kb2) * 2 + s) * 1024 + lane * 16);
;                   const LAS unsigned char* vb = lds + RT_V0 + bf * 32768 + (128 * wc + kap) * 128;
;     ...
;                   bf16x8 va[2], vc[2];
;                   RT_VRD(va, 0); __builtin_amdgcn_sched_barrier(0);
;                   RT_VRD(vc, 1); RT_VMM(va, 0); __builtin_amdgcn_sched_barrier(0);
;                   RT_VRD(va, 2); RT_VMM(vc, 1); __builtin_amdgcn_sched_barrier(0);
;                   RT_VRD(vc, 3); RT_VMM(va, 2); __builtin_amdgcn_sched_barrier(0);
;                   RT_VRD(va, 4); RT_VMM(vc, 3); __builtin_amdgcn_sched_barrier(0);
;                   RT_VRD(vc, 5); RT_VMM(va, 4); __builtin_amdgcn_sched_barrier(0);
;                   RT_VRD(va, 6); RT_VMM(vc, 5); __builtin_amdgcn_sched_barrier(0);
;                   RT_VRD(vc, 7); RT_VMM(va, 6); __builtin_amdgcn_sched_barrier(0);
;                   RT_VMM(vc, 7); __builtin_amdgcn_sched_barrier(0);
.LBB0_387:
	s_nop 6
	v_lshlrev_b32_e32 v98, 4, v0
	v_add_u32_e32 v99, s83, v98
	ds_write_b128 v99, v[190:193]
	ds_write_b128 v99, v[194:197] offset:1024
	s_lshl_b32 s12, s80, 6
	s_sub_i32 s12, 0x800, s12
	s_add_i32 s12, s12, s82
	v_add_u32_e32 v250, s12, v98
	ds_read_b128 v[242:245], v246 offset:4096
	ds_read_b128 v[106:109], v247 offset:4096
	s_waitcnt lgkmcnt(5)
	v_mfma_f32_32x32x16_bf16 v[82:97], v[234:237], v[190:193], v[82:97]
	s_waitcnt lgkmcnt(4)
	v_mfma_f32_32x32x16_bf16 v[82:97], v[238:241], v[194:197], v[82:97]
	ds_read_b128 v[234:237], v246 offset:8192
	ds_read_b128 v[238:241], v247 offset:8192
	s_waitcnt lgkmcnt(3)
	v_mfma_f32_32x32x16_bf16 v[66:81], v[242:245], v[190:193], v[66:81]
	s_waitcnt lgkmcnt(2)
	v_mfma_f32_32x32x16_bf16 v[66:81], v[106:109], v[194:197], v[66:81]
	ds_read_b128 v[242:245], v246 offset:12288
	ds_read_b128 v[106:109], v247 offset:12288
	s_waitcnt lgkmcnt(3)
	v_mfma_f32_32x32x16_bf16 v[50:65], v[234:237], v[190:193], v[50:65]
	s_waitcnt lgkmcnt(2)
	v_mfma_f32_32x32x16_bf16 v[50:65], v[238:241], v[194:197], v[50:65]
	ds_read_b128 v[234:237], v248
	ds_read_b128 v[238:241], v249
	s_barrier
	ds_read_b128 v[98:101], v250
	ds_read_b128 v[102:105], v250 offset:1024
	s_cmp_lg_u32 s80, 0
	s_cbranch_scc1 .Lrk_skip
	s_add_i32 s12, s30, 0x80
	s_cmp_eq_u32 s12, s11
	s_cbranch_scc1 .Lrk_skip
	s_add_i32 s13, s22, s6
	s_mov_b32 m0, s13
	s_add_i32 s12, s27, 0x10000
	buffer_load_dwordx4 v224, s[40:43], s12 offen lds
	s_add_i32 m0, s13, 0x2000
	s_add_i32 s12, s27, 0x20000
	buffer_load_dwordx4 v224, s[40:43], s12 offen lds
	s_add_i32 m0, s13, 0x4000
	s_add_i32 s12, s27, 0x30000
	buffer_load_dwordx4 v224, s[40:43], s12 offen lds
	s_add_i32 m0, s13, 0x6000
	s_add_i32 s12, s27, 0x40000
	buffer_load_dwordx4 v224, s[40:43], s12 offen lds
.Lrk_skip:
	s_waitcnt lgkmcnt(5)
	v_mfma_f32_32x32x16_bf16 v[34:49], v[242:245], v[190:193], v[34:49]
	s_waitcnt lgkmcnt(4)
	v_mfma_f32_32x32x16_bf16 v[34:49], v[106:109], v[194:197], v[34:49]
	ds_read_b128 v[242:245], v248 offset:4096
	ds_read_b128 v[106:109], v249 offset:4096
	s_waitcnt lgkmcnt(2)
	v_mfma_f32_32x32x16_bf16 v[82:97], v[234:237], v[98:101], v[82:97]
	v_mfma_f32_32x32x16_bf16 v[82:97], v[238:241], v[102:105], v[82:97]
	ds_read_b128 v[234:237], v248 offset:8192
	ds_read_b128 v[238:241], v249 offset:8192
	s_waitcnt lgkmcnt(3)
	v_mfma_f32_32x32x16_bf16 v[66:81], v[242:245], v[98:101], v[66:81]
	s_waitcnt lgkmcnt(2)
	v_mfma_f32_32x32x16_bf16 v[66:81], v[106:109], v[102:105], v[66:81]
	ds_read_b128 v[242:245], v248 offset:12288
	ds_read_b128 v[106:109], v249 offset:12288
	s_waitcnt lgkmcnt(3)
	v_mfma_f32_32x32x16_bf16 v[50:65], v[234:237], v[98:101], v[50:65]
	s_waitcnt lgkmcnt(2)
	v_mfma_f32_32x32x16_bf16 v[50:65], v[238:241], v[102:105], v[50:65]
	s_waitcnt lgkmcnt(1)
	v_mfma_f32_32x32x16_bf16 v[34:49], v[242:245], v[98:101], v[34:49]
	s_waitcnt lgkmcnt(0)
	v_mfma_f32_32x32x16_bf16 v[34:49], v[106:109], v[102:105], v[34:49]
	s_cmp_eq_u32 s80, 0
	s_cbranch_scc1 .Lkb_skip
	s_add_i32 s12, s30, 0x80
	s_cmp_eq_u32 s12, s11
	s_cbranch_scc1 .Lkb_skip
	s_add_i32 s13, s22, s6
	s_mov_b32 m0, s13
	s_add_i32 s12, s27, 0x10000
	buffer_load_dwordx4 v224, s[40:43], s12 offen lds
	s_add_i32 m0, s13, 0x2000
	s_add_i32 s12, s27, 0x20000
	buffer_load_dwordx4 v224, s[40:43], s12 offen lds
	s_add_i32 m0, s13, 0x4000
	s_add_i32 s12, s27, 0x30000
	buffer_load_dwordx4 v224, s[40:43], s12 offen lds
	s_add_i32 m0, s13, 0x6000
	s_add_i32 s12, s27, 0x40000
	buffer_load_dwordx4 v224, s[40:43], s12 offen lds
